# retention: Kt/Vt tiles of step t+1 prefetched during step t into spare VGPRs, step top no longer waits for the previous step's O stores
# baseline (speedup 1.0000x reference)
.LBB0_60:
	s_and_b64 s[4:5], s[40:41], exec
	s_mov_b32 s4, 0x2d39b600
	s_cselect_b32 s4, s4, 0x3239b600
	v_readlane_b32 s5, v254, 47
	s_add_u32 s38, s5, s4
	v_readlane_b32 s4, v254, 49
	s_addc_u32 s39, s4, 0
	s_lshr_b32 s69, s99, 7
	s_add_i32 s14, s69, -1
	s_lshl_b32 s6, s14, 7
	s_and_b64 s[4:5], s[40:41], exec
	s_cselect_b32 s4, 0, s6
	s_add_i32 s4, s4, s98
	s_ashr_i32 s5, s4, 31
	s_lshl_b64 s[4:5], s[4:5], 10
	v_readlane_b32 s42, v254, 41
	s_mov_b32 s34, s44
	s_add_u32 s6, s42, s4
	v_readlane_b32 s43, v254, 42
	v_writelane_b32 v254, s34, 39
	s_addc_u32 s33, s43, s5
	v_writelane_b32 v255, s48, 13
	v_writelane_b32 v254, s35, 40
	s_lshl_b32 s34, s44, 8
	s_add_u32 s36, s6, s34
	s_addc_u32 s37, s33, 0
	v_lshl_add_u64 v[2:3], s[36:37], 0, v[130:131]
	s_mov_b32 s33, 0x8000
	v_add_co_u32_e32 v4, vcc, s33, v2
	v_readlane_b32 s44, v254, 43
	s_nop 0
	v_addc_co_u32_e32 v5, vcc, 0, v3, vcc
	s_mov_b32 s36, 0x10000
	s_add_u32 s4, s44, s4
	v_readlane_b32 s45, v254, 44
	global_load_dwordx4 v[64:67], v[2:3], off
	global_load_dwordx4 v[68:71], v[4:5], off
	v_add_co_u32_e32 v4, vcc, s36, v2
	s_addc_u32 s5, s45, s5
	s_nop 0
	v_addc_co_u32_e32 v5, vcc, 0, v3, vcc
	s_mov_b32 s6, 0x18000
	s_add_u32 s4, s4, s34
	v_add_co_u32_e32 v2, vcc, s6, v2
	s_addc_u32 s5, s5, 0
	s_nop 0
	v_addc_co_u32_e32 v3, vcc, 0, v3, vcc
	global_load_dwordx4 v[72:75], v[4:5], off
	global_load_dwordx4 v[76:79], v[2:3], off
	v_lshl_add_u64 v[2:3], s[4:5], 0, v[130:131]
	v_add_co_u32_e32 v4, vcc, s33, v2
	s_add_u32 s68, s42, s34
	s_nop 0
	v_addc_co_u32_e32 v5, vcc, 0, v3, vcc
	global_load_dwordx4 v[80:83], v[2:3], off
	global_load_dwordx4 v[84:87], v[4:5], off
	v_add_co_u32_e32 v4, vcc, s36, v2
	v_readlane_b32 s4, v254, 45
	s_nop 0
	v_addc_co_u32_e32 v5, vcc, 0, v3, vcc
	v_add_co_u32_e32 v2, vcc, s6, v2
	s_addc_u32 s6, s43, 0
	s_nop 0
	v_addc_co_u32_e32 v3, vcc, 0, v3, vcc
	global_load_dwordx4 v[88:91], v[4:5], off
	global_load_dwordx4 v[92:95], v[2:3], off
	s_add_u32 s94, s44, s34
	s_addc_u32 s95, s45, 0
	s_lshl_b64 s[0:1], s[0:1], 1
	s_add_u32 s72, s4, s0
	v_readlane_b32 s0, v254, 46
	s_addc_u32 s73, s0, s1
	s_lshl_b64 s[0:1], s[20:21], 1
	v_readlane_b32 s4, v254, 48
	s_add_u32 s74, s4, s0
	v_readlane_b32 s0, v254, 50
	s_addc_u32 s75, s0, s1
	s_lshl_b32 s66, s99, 5
	s_lshl_b32 s67, s99, 6
	s_and_b64 s[0:1], s[40:41], exec
	v_readlane_b32 s0, v254, 55
	s_cselect_b32 s64, s0, 8
	s_lshl_b64 s[0:1], s[34:35], 1
	s_add_u32 s4, s38, s0
	s_addc_u32 s5, s39, s1
	s_lshl_b64 s[0:1], s[48:49], 1
	s_add_u32 s76, s4, s0
	s_addc_u32 s77, s5, s1
	v_readlane_b32 s0, v254, 56
	v_mul_f32_e32 v0, 0x43000000, v32
	v_readlane_b32 s1, v254, 57
	v_exp_f32_e32 v134, v0
	v_writelane_b32 v255, s49, 14
	v_cndmask_b32_e64 v0, 0, 1, s[0:1]
	v_readlane_b32 s0, v254, 58
	v_readlane_b32 s1, v254, 59
	s_mul_i32 s71, s99, 0x60
	s_mov_b32 s85, 0x8000
	v_cndmask_b32_e64 v2, 0, 1, s[0:1]
	s_and_b64 s[0:1], s[40:41], exec
	v_readfirstlane_b32 s0, v2
	v_readfirstlane_b32 s1, v0
	s_cselect_b32 s0, s0, s1
	s_bitcmp1_b32 s0, 0
	s_cselect_b64 s[0:1], -1, 0
	s_xor_b64 s[88:89], s[0:1], -1
	s_and_b64 s[0:1], s[40:41], exec
	v_readlane_b32 s0, v254, 61
	v_readlane_b32 s1, v254, 60
	s_cselect_b32 s0, s1, s0
	s_cmp_eq_u32 s0, 0
	v_readlane_b32 s0, v254, 62
	v_readlane_b32 s1, v254, 63
	s_cselect_b64 s[90:91], -1, 0
	s_mov_b32 s84, 0x18000
	v_cndmask_b32_e64 v0, 0, 1, s[0:1]
	v_readlane_b32 s0, v255, 0
	v_readlane_b32 s1, v255, 1
	s_mov_b32 s33, 1
	v_mov_b32_e32 v136, v134
	v_cndmask_b32_e64 v2, 0, 1, s[0:1]
	v_cndmask_b32_e64 v0, v0, v2, s[40:41]
	v_and_b32_e32 v0, 1, v0
	v_cmp_eq_u32_e32 vcc, 1, v0
	s_xor_b64 s[38:39], vcc, -1
	s_and_b64 s[0:1], s[40:41], exec
	v_readlane_b32 s0, v255, 3
	v_readlane_b32 s1, v255, 2
	s_cselect_b32 s0, s1, s0
	s_cmp_eq_u32 s0, 0
	v_readlane_b32 s0, v255, 4
	v_readlane_b32 s1, v255, 5
	s_cselect_b64 s[36:37], -1, 0
	s_or_b64 s[4:5], s[40:41], s[0:1]
	s_cmp_gt_i32 s64, 0
	s_cselect_b64 s[0:1], -1, 0
	s_and_b64 s[0:1], s[4:5], s[0:1]
	s_cmp_gt_i32 s64, 1
	s_cselect_b64 s[20:21], -1, 0
	s_and_b64 s[42:43], s[4:5], s[20:21]
	v_readlane_b32 s4, v255, 6
	v_readlane_b32 s5, v255, 7
	s_or_b64 s[4:5], s[40:41], s[4:5]
	s_cmp_gt_i32 s64, 2
	s_cselect_b64 s[20:21], -1, 0
	s_and_b64 s[44:45], s[4:5], s[20:21]
	s_cmp_gt_i32 s64, 3
	s_cselect_b64 s[20:21], -1, 0
	s_and_b64 s[48:49], s[4:5], s[20:21]
	v_readlane_b32 s4, v255, 8
	v_readlane_b32 s5, v255, 9
	s_or_b64 s[4:5], s[40:41], s[4:5]
	s_cmp_gt_i32 s64, 4
	s_cselect_b64 s[20:21], -1, 0
	s_and_b64 s[50:51], s[4:5], s[20:21]
	s_cmp_gt_i32 s64, 5
	s_cselect_b64 s[20:21], -1, 0
	s_and_b64 s[52:53], s[4:5], s[20:21]
	v_readlane_b32 s4, v255, 10
	v_readlane_b32 s5, v255, 11
	s_or_b64 s[4:5], s[40:41], s[4:5]
	s_cmp_gt_i32 s64, 6
	s_cselect_b64 s[20:21], -1, 0
	s_and_b64 s[62:63], s[4:5], s[20:21]
	s_cmp_gt_i32 s64, 7
	s_cselect_b64 s[20:21], -1, 0
	s_and_b64 s[64:65], s[4:5], s[20:21]
	v_mov_b32_e32 v137, v134
	s_lshl_b32 s34, s66, 1
	s_lshl_b32 s70, s67, 1
	s_lshl_b32 s20, s71, 1
	s_and_b64 s[4:5], s[40:41], exec
	s_cselect_b32 s4, 0, s14
	s_lshl_b32 s4, s4, 7
	v_mov_b32_e32 v210, s4
	v_lshlrev_b32_e32 v211, 3, v162
	v_mul_lo_u32 v212, v161, s99
	v_add3_u32 v211, v212, v211, v210
	v_lshlrev_b32_e32 v211, 1, v211
	v_add_u32_e32 v212, s34, v211
	v_add_u32_e32 v213, s70, v211
	v_add_u32_e32 v214, s20, v211
	global_load_dwordx4 v[186:189], v211, s[72:73]
	global_load_dwordx4 v[190:193], v212, s[72:73]
	global_load_dwordx4 v[194:197], v213, s[72:73]
	global_load_dwordx4 v[198:201], v214, s[72:73]
	global_load_dwordx4 v[202:205], v211, s[74:75]
	global_load_dwordx4 v[206:209], v212, s[74:75]
	s_branch .LBB0_62

.LBB0_62:
	s_add_i32 s21, s33, -1
	s_and_b64 s[4:5], s[40:41], exec
	s_cselect_b32 s4, s21, s14
	v_mov_b32_e32 v135, v96
	v_mov_b32_e32 v164, v152
	v_mov_b32_e32 v167, v161
	v_mov_b32_e32 v34, v162
	s_lshl_b32 s66, s4, 7
	s_ashr_i32 s67, s66, 31
	v_lshlrev_b32_e32 v0, 3, v34
	s_lshl_b64 s[4:5], s[66:67], 1
	s_add_u32 s78, s72, s4
	s_addc_u32 s79, s73, s5
	s_add_u32 s4, s74, s4
	s_addc_u32 s5, s75, s5
	s_mov_b32 s71, s35
	s_mov_b32 s21, s35
	v_add_u32_e32 v14, s17, v135
	s_movk_i32 s4, 0x110
	v_mul_lo_u32 v168, v14, s4
	v_readlane_b32 s5, v254, 13
	v_lshlrev_b32_e32 v171, 3, v164
	s_cmp_lg_u32 s33, 1
	s_cbranch_scc1 .Lret_steady
	s_waitcnt vmcnt(0)
	s_branch .Lret_cont
.Lret_steady:
	s_waitcnt vmcnt(16)
.Lret_cont:
	v_cvt_pk_bf16_f32 v15, v18, v19
	v_add_u32_e32 v166, s5, v168
	v_add3_u32 v35, v166, v171, s7
	v_cvt_pk_bf16_f32 v14, v16, v17
	v_cvt_pk_bf16_f32 v33, v22, v23
	v_cvt_pk_bf16_f32 v32, v20, v21
	ds_write2_b64 v35, v[14:15], v[32:33] offset1:2
	v_cvt_pk_bf16_f32 v15, v26, v27
	v_cvt_pk_bf16_f32 v14, v24, v25
	v_cvt_pk_bf16_f32 v33, v30, v31
	v_cvt_pk_bf16_f32 v32, v28, v29
	ds_write2_b64 v35, v[14:15], v[32:33] offset0:4 offset1:6
	v_mul_lo_u32 v169, v167, s4
	v_lshlrev_b32_e32 v170, 4, v34
	v_add_u32_e32 v15, s18, v135
	v_add3_u32 v14, 0, v169, v170
	v_mul_lo_u32 v163, v15, s4
	ds_write_b128 v14, v[64:67]
	ds_write_b128 v14, v[68:71] offset:8704
	ds_write_b128 v14, v[72:75] offset:17408
	ds_write_b128 v14, v[76:79] offset:26112
	ds_write_b128 v14, v[80:83] offset:34816
	ds_write_b128 v14, v[84:87] offset:43520
	ds_write_b128 v14, v[88:91] offset:52224
	ds_write_b128 v14, v[92:95] offset:60928
	v_lshlrev_b32_e32 v14, 2, v135
	v_readlane_b32 s5, v254, 11
	v_lshlrev_b32_e32 v133, 4, v164
	v_add_u32_e32 v172, 0, v163
	v_readlane_b32 s4, v254, 12
	v_add_u32_e32 v175, s5, v14
	v_add_u32_e32 v148, 0, v133
	s_movk_i32 s21, 0x110
	v_add_u32_e32 v176, s4, v14
	v_add_u32_e32 v150, s5, v133
	v_add_u32_e32 v174, s4, v133
	v_lshlrev_b32_e32 v173, 2, v164
	s_mov_b64 s[4:5], -1
	s_and_b64 vcc, exec, s[88:89]
	v_add_u32_e32 v165, v172, v133
	s_waitcnt lgkmcnt(0)
	s_barrier
	s_cbranch_vccz .LBB0_65
	v_add_u32_e32 v14, s9, v135
	v_mad_u64_u32 v[14:15], s[4:5], v14, s21, v[148:149]
	ds_read_b128 v[32:35], v14 offset:34816
	ds_read_b128 v[60:63], v14 offset:34848
	ds_read_b128 v[36:39], v165
	ds_read_b128 v[138:141], v165 offset:32
	s_andn2_b64 vcc, exec, s[90:91]
	s_waitcnt lgkmcnt(1)
	v_mfma_f32_32x32x16_bf16 v[32:47], v[32:35], v[36:39], 0
	s_waitcnt lgkmcnt(0)
	v_mfma_f32_32x32x16_bf16 v[32:47], v[60:63], v[138:141], v[32:47]
	ds_read_b128 v[60:63], v14 offset:34880
	ds_read_b128 v[138:141], v165 offset:64
	s_waitcnt lgkmcnt(0)
	v_mfma_f32_32x32x16_bf16 v[32:47], v[60:63], v[138:141], v[32:47]
	ds_read_b128 v[60:63], v14 offset:34912
	ds_read_b128 v[138:141], v165 offset:96
	s_waitcnt lgkmcnt(0)
	v_mfma_f32_32x32x16_bf16 v[32:47], v[60:63], v[138:141], v[32:47]
	ds_read_b128 v[60:63], v14 offset:34944
	ds_read_b128 v[138:141], v165 offset:128
	s_waitcnt lgkmcnt(0)
	v_mfma_f32_32x32x16_bf16 v[32:47], v[60:63], v[138:141], v[32:47]
	ds_read_b128 v[60:63], v14 offset:34976
	ds_read_b128 v[138:141], v165 offset:160
	s_waitcnt lgkmcnt(0)
	v_mfma_f32_32x32x16_bf16 v[32:47], v[60:63], v[138:141], v[32:47]
	ds_read_b128 v[60:63], v14 offset:35008
	ds_read_b128 v[138:141], v165 offset:192
	s_waitcnt lgkmcnt(0)
	v_mfma_f32_32x32x16_bf16 v[32:47], v[60:63], v[138:141], v[32:47]
	ds_read_b128 v[60:63], v14 offset:35040
	ds_read_b128 v[138:141], v165 offset:224
	v_add_u32_e32 v14, s10, v175
	v_cndmask_b32_e64 v14, v176, v14, s[40:41]
	ds_read_b32 v146, v14
	v_add_u32_e32 v14, s15, v150
	v_cndmask_b32_e64 v147, v14, v174, s[40:41]
	s_waitcnt lgkmcnt(1)
	v_mfma_f32_32x32x16_bf16 v[32:47], v[60:63], v[138:141], v[32:47]
	ds_read_b128 v[60:63], v147
	ds_read_b128 v[138:141], v147 offset:32
	s_waitcnt lgkmcnt(1)
	v_mul_f32_e64 v14, v146, v60
	v_mul_f32_e64 v15, v146, v61
	s_nop 6
	v_pk_mul_f32 v[14:15], v[32:33], v[14:15]
	v_pk_mul_f32 v[32:33], v[146:147], v[62:63] op_sel_hi:[0,1]
	v_pk_mul_f32 v[142:143], v[34:35], v[32:33]
	s_waitcnt lgkmcnt(0)
	v_pk_mul_f32 v[32:33], v[146:147], v[138:139] op_sel_hi:[0,1]
	v_pk_mul_f32 v[62:63], v[36:37], v[32:33]
	v_pk_mul_f32 v[32:33], v[146:147], v[140:141] op_sel_hi:[0,1]
	v_pk_mul_f32 v[144:145], v[38:39], v[32:33]
	ds_read_b128 v[32:35], v147 offset:64
	s_waitcnt lgkmcnt(0)
	v_pk_mul_f32 v[32:33], v[146:147], v[32:33] op_sel_hi:[0,1]
	v_pk_mul_f32 v[60:61], v[40:41], v[32:33]
	v_pk_mul_f32 v[32:33], v[146:147], v[34:35] op_sel_hi:[0,1]
	v_pk_mul_f32 v[140:141], v[42:43], v[32:33]
	ds_read_b128 v[32:35], v147 offset:96
	s_waitcnt lgkmcnt(0)
	v_pk_mul_f32 v[32:33], v[146:147], v[32:33] op_sel_hi:[0,1]
	v_pk_mul_f32 v[138:139], v[44:45], v[32:33]
	v_pk_mul_f32 v[32:33], v[146:147], v[34:35] op_sel_hi:[0,1]
	v_pk_mul_f32 v[146:147], v[46:47], v[32:33]
	s_cbranch_vccz .LBB0_90
	s_cbranch_execnz .LBB0_67
	s_branch .LBB0_66

.LBB0_72:
	v_add3_u32 v46, v172, v171, s8
	v_cvt_pk_bf16_f32 v45, v142, v143
	v_cvt_pk_bf16_f32 v44, v14, v15
	v_cvt_pk_bf16_f32 v15, v144, v145
	v_cvt_pk_bf16_f32 v14, v62, v63
	v_add_u32_e32 v46, 0x8800, v46
	s_barrier
	ds_write2_b64 v46, v[44:45], v[14:15] offset1:2
	v_cvt_pk_bf16_f32 v15, v140, v141
	v_cvt_pk_bf16_f32 v14, v60, v61
	v_cvt_pk_bf16_f32 v45, v146, v147
	v_cvt_pk_bf16_f32 v44, v138, v139
	ds_write2_b64 v46, v[14:15], v[44:45] offset0:4 offset1:6
	v_cvt_pk_bf16_f32 v15, v148, v149
	v_cvt_pk_bf16_f32 v14, v32, v33
	v_cvt_pk_bf16_f32 v33, v150, v151
	v_cvt_pk_bf16_f32 v32, v34, v35
	ds_write2_b64 v46, v[14:15], v[32:33] offset0:8 offset1:10
	v_cvt_pk_bf16_f32 v15, v40, v41
	v_cvt_pk_bf16_f32 v14, v36, v37
	v_cvt_pk_bf16_f32 v33, v42, v43
	v_cvt_pk_bf16_f32 v32, v38, v39
	ds_write2_b64 v46, v[14:15], v[32:33] offset0:12 offset1:14
	v_lshl_add_u32 v14, v0, 2, 0
	v_add_u32_e32 v36, 0x22000, v14
	ds_read_b128 v[32:35], v36
	v_mov_b32_e32 v56, v186
	v_mov_b32_e32 v57, v187
	v_mov_b32_e32 v58, v188
	v_mov_b32_e32 v59, v189
	v_mov_b32_e32 v52, v190
	v_mov_b32_e32 v53, v191
	v_mov_b32_e32 v54, v192
	v_mov_b32_e32 v55, v193
	v_mov_b32_e32 v48, v194
	v_mov_b32_e32 v49, v195
	v_mov_b32_e32 v50, v196
	v_mov_b32_e32 v51, v197
	v_mov_b32_e32 v10, v198
	v_mov_b32_e32 v11, v199
	v_mov_b32_e32 v12, v200
	v_mov_b32_e32 v13, v201
	v_mov_b32_e32 v6, v202
	v_mov_b32_e32 v7, v203
	v_mov_b32_e32 v8, v204
	v_mov_b32_e32 v9, v205
	v_mov_b32_e32 v2, v206
	v_mov_b32_e32 v3, v207
	v_mov_b32_e32 v4, v208
	v_mov_b32_e32 v5, v209
	v_lshlrev_b32_e32 v14, 16, v56
	v_and_b32_e32 v15, 0xffff0000, v56
	v_lshlrev_b32_e32 v40, 16, v52
	v_and_b32_e32 v41, 0xffff0000, v52
	ds_read_b128 v[36:39], v36 offset:16
	s_waitcnt lgkmcnt(1)
	v_pk_mul_f32 v[14:15], v[32:33], v[14:15]
	v_lshlrev_b32_e32 v44, 16, v48
	v_and_b32_e32 v45, 0xffff0000, v48
	v_lshlrev_b32_e32 v62, 16, v10
	v_and_b32_e32 v63, 0xffff0000, v10
	v_cvt_pk_bf16_f32 v10, v14, v15
	v_pk_mul_f32 v[14:15], v[32:33], v[40:41]
	v_lshlrev_b32_e32 v42, 16, v57
	v_and_b32_e32 v43, 0xffff0000, v57
	v_cvt_pk_bf16_f32 v40, v14, v15
	v_pk_mul_f32 v[14:15], v[32:33], v[44:45]
	v_lshlrev_b32_e32 v52, 16, v53
	v_and_b32_e32 v53, 0xffff0000, v53
	v_cvt_pk_bf16_f32 v44, v14, v15
	v_pk_mul_f32 v[14:15], v[32:33], v[62:63]
	v_pk_mul_f32 v[42:43], v[34:35], v[42:43]
	v_lshlrev_b32_e32 v46, 16, v58
	v_and_b32_e32 v47, 0xffff0000, v58
	v_lshlrev_b32_e32 v48, 16, v49
	v_and_b32_e32 v49, 0xffff0000, v49
	v_cvt_pk_bf16_f32 v32, v14, v15
	v_lshlrev_b32_e32 v14, 16, v11
	v_and_b32_e32 v15, 0xffff0000, v11
	v_cvt_pk_bf16_f32 v11, v42, v43
	v_pk_mul_f32 v[42:43], v[34:35], v[52:53]
	v_lshlrev_b32_e32 v56, 16, v59
	v_and_b32_e32 v57, 0xffff0000, v59
	v_lshlrev_b32_e32 v58, 16, v54
	v_and_b32_e32 v59, 0xffff0000, v54
	v_cvt_pk_bf16_f32 v41, v42, v43
	v_pk_mul_f32 v[42:43], v[34:35], v[48:49]
	v_pk_mul_f32 v[14:15], v[34:35], v[14:15]
	s_waitcnt lgkmcnt(0)
	v_pk_mul_f32 v[34:35], v[36:37], v[46:47]
	v_lshlrev_b32_e32 v60, 16, v50
	v_and_b32_e32 v61, 0xffff0000, v50
	v_cvt_pk_bf16_f32 v33, v14, v15
	v_lshlrev_b32_e32 v14, 16, v12
	v_and_b32_e32 v15, 0xffff0000, v12
	v_cvt_pk_bf16_f32 v12, v34, v35
	v_pk_mul_f32 v[34:35], v[36:37], v[58:59]
	v_cvt_pk_bf16_f32 v45, v42, v43
	v_cvt_pk_bf16_f32 v42, v34, v35
	v_pk_mul_f32 v[34:35], v[36:37], v[60:61]
	v_pk_mul_f32 v[14:15], v[36:37], v[14:15]
	v_lshlrev_b32_e32 v54, 16, v55
	v_and_b32_e32 v55, 0xffff0000, v55
	v_cvt_pk_bf16_f32 v46, v34, v35
	v_cvt_pk_bf16_f32 v34, v14, v15
	v_lshlrev_b32_e32 v14, 16, v13
	v_and_b32_e32 v15, 0xffff0000, v13
	v_pk_mul_f32 v[36:37], v[38:39], v[56:57]
	v_lshlrev_b32_e32 v50, 16, v51
	v_and_b32_e32 v51, 0xffff0000, v51
	v_cvt_pk_bf16_f32 v13, v36, v37
	v_pk_mul_f32 v[36:37], v[38:39], v[54:55]
	v_pk_mul_f32 v[14:15], v[38:39], v[14:15]
	v_readlane_b32 s4, v254, 8
	v_cvt_pk_bf16_f32 v43, v36, v37
	v_pk_mul_f32 v[36:37], v[38:39], v[50:51]
	v_cvt_pk_bf16_f32 v35, v14, v15
	v_add3_u32 v14, s4, v169, v170
	v_readlane_b32 s4, v254, 14
	v_cvt_pk_bf16_f32 v47, v36, v37
	ds_write_b128 v14, v[10:13]
	ds_write_b128 v14, v[40:43] offset:8704
	ds_write_b128 v14, v[44:47] offset:17408
	ds_write_b128 v14, v[32:35] offset:26112
	v_add3_u32 v10, s4, v169, v170
	s_cmp_ge_u32 s33, s69
	ds_write_b128 v10, v[6:9]
	ds_write_b128 v10, v[2:5] offset:8704
	s_cbranch_scc1 .LBB0_74
	s_add_i32 s21, s14, -1
	s_and_b64 s[4:5], s[40:41], exec
	s_cselect_b32 s4, s33, s21
	s_lshl_b32 s4, s4, 7
	v_mov_b32_e32 v210, s4
	s_add_i32 s4, s4, s98
	s_ashr_i32 s5, s4, 31
	s_lshl_b64 s[4:5], s[4:5], 10
	s_add_u32 s78, s68, s4
	v_lshl_add_u32 v0, v167, 9, v0
	s_addc_u32 s79, s6, s5
	v_lshlrev_b64 v[2:3], 1, v[0:1]
	v_lshl_add_u64 v[4:5], s[78:79], 0, v[2:3]
	v_add_co_u32_e32 v6, vcc, s85, v4
	s_add_u32 s4, s94, s4
	s_nop 0
	v_addc_co_u32_e32 v7, vcc, 0, v5, vcc
	global_load_dwordx4 v[64:67], v[4:5], off
	global_load_dwordx4 v[68:71], v[6:7], off
	v_add_co_u32_e32 v6, vcc, 0x10000, v4
	s_addc_u32 s5, s95, s5
	s_nop 0
	v_addc_co_u32_e32 v7, vcc, 0, v5, vcc
	v_add_co_u32_e32 v4, vcc, s84, v4
	v_lshl_add_u64 v[2:3], s[4:5], 0, v[2:3]
	s_nop 0
	v_addc_co_u32_e32 v5, vcc, 0, v5, vcc
	global_load_dwordx4 v[72:75], v[6:7], off
	global_load_dwordx4 v[76:79], v[4:5], off
	v_add_co_u32_e32 v4, vcc, 0x8000, v2
	s_nop 1
	v_addc_co_u32_e32 v5, vcc, 0, v3, vcc
	global_load_dwordx4 v[80:83], v[2:3], off
	global_load_dwordx4 v[84:87], v[4:5], off
	v_add_co_u32_e32 v4, vcc, 0x10000, v2
	s_nop 1
	v_addc_co_u32_e32 v5, vcc, 0, v3, vcc
	v_add_co_u32_e32 v2, vcc, 0x18000, v2
	s_nop 1
	v_addc_co_u32_e32 v3, vcc, 0, v3, vcc
	global_load_dwordx4 v[88:91], v[4:5], off
	global_load_dwordx4 v[92:95], v[2:3], off
	v_lshlrev_b32_e32 v211, 3, v162
	v_mul_lo_u32 v212, v161, s99
	v_add3_u32 v211, v212, v211, v210
	v_lshlrev_b32_e32 v211, 1, v211
	v_add_u32_e32 v212, s34, v211
	v_add_u32_e32 v213, s70, v211
	v_add_u32_e32 v214, s20, v211
	global_load_dwordx4 v[186:189], v211, s[72:73]
	global_load_dwordx4 v[190:193], v212, s[72:73]
	global_load_dwordx4 v[194:197], v213, s[72:73]
	global_load_dwordx4 v[198:201], v214, s[72:73]
	global_load_dwordx4 v[202:205], v211, s[74:75]
	global_load_dwordx4 v[206:209], v212, s[74:75]
